# grid barrier poll back-off: s_sleep 3 instead of s_sleep 1 between polls (v58 otherwise)
# baseline (speedup 1.0000x reference)
; DEV unsigned xb_ld(unsigned* p)              { return __hip_atomic_load(p, __ATOMIC_RELAXED, __HIP_MEMORY_SCOPE_AGENT); }
; DEV unsigned xb_add(unsigned* p, unsigned v) { return __hip_atomic_fetch_add(p, v, __ATOMIC_RELAXED, __HIP_MEMORY_SCOPE_AGENT); }
; #define XB_SPIN(cond, bar) do { unsigned _sp = 0; while (cond) { __builtin_amdgcn_s_sleep(1); \
;     if ((++_sp & 255u) == 0u) { if (xb_ld(&(bar)[XB_TMO])) break; if (_sp > XB_SPIN_CAP) { atomicAdd(&(bar)[XB_TMO], 1u); break; } } } } while (0)
; DEV void xcd_barrier(const XcdBarrier& b) {
;     ...
;       const unsigned og = xb_add(&bar[XB_TOP], 1u);
;       const unsigned tg = og / nx;
;       if (og + 1u == (tg + 1u) * nx) xb_add(&bar[XB_TOPGEN], 1u);
;       else XB_SPIN(xb_ld(&bar[XB_TOPGEN]) == tg, bar);
.Lbar_poll:
	global_load_dword v5, v169, s[8:9] sc1
	s_add_i32 s12, s12, 1
	s_waitcnt vmcnt(0)
	v_cmp_ge_u32_e32 vcc, v5, v1
	s_cbranch_vccnz .Lbar_done
	s_cmp_lt_u32 s12, 0x200000
	s_cbranch_scc0 .Lbar_done
	s_sleep 3
	s_branch .Lbar_poll
